# grid barrier: XCD leader publishes its generation word before waiting on its own acquire invalidate
# speedup vs baseline: 1.0025x; 1.0025x over previous
.LBB0_1001:
	s_or_b64 exec, exec, s[2:3]
	s_mov_b64 s[2:3], exec
	v_mbcnt_lo_u32_b32 v0, s2, 0
	v_mbcnt_hi_u32_b32 v0, s3, v0
	v_cmp_eq_u32_e32 vcc, 0, v0
	s_and_saveexec_b64 s[4:5], vcc
	s_cbranch_execz .Lxb_inv
	s_bcnt1_i32_b64 s2, s[2:3]
	v_mov_b32_e32 v0, s2
	v_readlane_b32 s2, v255, 3
	v_readlane_b32 s3, v255, 4
	s_nop 4
	global_atomic_add v81, v0, s[2:3]
.Lxb_inv:
	s_or_b64 exec, exec, s[4:5]
	s_waitcnt vmcnt(0)
	buffer_inv sc1
	s_branch .Ltr_19
